# FoX: stagger the two 4-wave teams by half a key-tile iteration (extra mid-iteration s_barrier; team1 +1 barrier before loop, team0 +1 after) so one team's MFMA phase overlaps the other's softmax/LDS p
# baseline (speedup 1.0000x reference)
; DI void fox_attn(const Params& P, int bh, int qb, unsigned char* smem, int tt) {
;     ...
;     const float cq = cf[q] * L2E;
;     float m = -1e30f, l = 0.f;
;     f32x16 O[2];
; #pragma unroll
;     for (int e = 0; e < 16; ++e) { O[0][e] = 0.f; O[1][e] = 0.f; }
;     const int ntiles = 2 * qb + 2;
;     const int srow = tid >> 3, scol = (tid & 7) * 8;
;     const bf16_t* kg = fqk + ((size_t)b * TSEQ + srow) * 1024 + 512 + hh * 64 + scol;
;     const bf16_t* vg = vT + (size_t)srow * TSEQ + scol;
;     u32x4 rk0, rk1, rv0, rv1; float rc = 0.f;
;     rk0 = *(const u32x4*)kg; rk1 = *(const u32x4*)(kg + 32 * 1024);
;     rv0 = *(const u32x4*)vg; rv1 = *(const u32x4*)(vg + 32 * TSEQ);
;     if (tid < 64) rc = cf[tid] * L2E;
;     {
;         bf16_t* Ks = (bf16_t*)smem; bf16_t* VTs = Ks + 64 * 72; float* cks = (float*)(smem + 2 * 64 * 72 * 2);
;         *(u32x4*)(Ks + srow * 72 + scol) = rk0; *(u32x4*)(Ks + (srow + 32) * 72 + scol) = rk1;
;         *(u32x4*)(VTs + srow * 72 + scol) = rv0; *(u32x4*)(VTs + (srow + 32) * 72 + scol) = rv1;
;         if (tid < 64) cks[tid] = rc;
;     }
;     __syncthreads();
.LBB0_542:
	s_or_b64 exec, exec, s[2:3]
	v_mul_u32_u24_e32 v0, 0x48, v2
	v_lshlrev_b32_e32 v119, 1, v0
	v_add3_u32 v0, v131, v119, v104
	s_waitcnt vmcnt(4)
	ds_write_b128 v0, v[82:85]
	s_waitcnt vmcnt(3)
	ds_write_b128 v0, v[86:89] offset:4608
	s_waitcnt vmcnt(1)
	ds_write_b128 v0, v[90:93] offset:9216
	s_waitcnt vmcnt(0)
	ds_write_b128 v0, v[94:97] offset:13824
	s_and_saveexec_b64 s[2:3], s[0:1]
	v_lshl_add_u32 v0, v130, 2, v131
	ds_write_b32 v0, v118 offset:18432
	s_or_b64 exec, exec, s[2:3]
	v_lshlrev_b32_e32 v0, 3, v23
	v_mul_f32_e32 v121, 0x3fb8aa3b, v3
	v_lshlrev_b32_e32 v105, 2, v23
	v_lshlrev_b32_e32 v3, 2, v14
	v_lshl_add_u32 v125, v0, 1, v131
	v_sub_u32_e32 v126, 0, v0
	v_add_u32_e32 v0, v9, v22
	v_xor_b32_e32 v99, 0x80, v3
	v_sub_u32_e32 v0, v0, v105
	v_lshlrev_b32_e32 v3, 7, v8
	v_sub_u32_e32 v0, v0, v3
	v_lshlrev_b64 v[4:5], 22, v[4:5]
	v_add_u32_e32 v127, 0x780, v0
	v_lshl_or_b32 v0, v2, 11, v4
	v_lshlrev_b32_e32 v2, 1, v12
	v_and_b32_e32 v3, 7, v10
	v_and_b32_e32 v2, 0x380, v2
	v_lshlrev_b32_e32 v3, 4, v3
	v_or3_b32 v4, v0, v2, v3
	v_mov_b32_e32 v14, v1
	v_mov_b32_e32 v15, v1
	v_lshlrev_b64 v[100:101], 10, v[6:7]
	v_lshlrev_b32_e32 v122, 1, v11
	v_mul_u32_u24_e32 v124, 0x48, v22
	v_lshl_add_u64 v[108:109], s[10:11], 0, v[4:5]
	v_mov_b32_e32 v0, v1
	v_mov_b32_e32 v2, v1
	v_mov_b32_e32 v3, v1
	v_mov_b32_e32 v4, v1
	v_mov_b32_e32 v5, v1
	v_mov_b32_e32 v6, v1
	v_mov_b32_e32 v7, v1
	v_mov_b32_e32 v8, v1
	v_mov_b32_e32 v9, v1
	v_mov_b32_e32 v10, v1
	v_mov_b32_e32 v11, v1
	v_mov_b32_e32 v12, v1
	v_mov_b32_e32 v13, v1
	v_mov_b64_e32 v[32:33], v[14:15]
	v_mov_b64_e32 v[30:31], v[12:13]
	v_mov_b64_e32 v[28:29], v[10:11]
	v_mov_b64_e32 v[26:27], v[8:9]
	v_mov_b64_e32 v[24:25], v[6:7]
	v_mov_b64_e32 v[22:23], v[4:5]
	v_mov_b64_e32 v[20:21], v[2:3]
	v_mov_b64_e32 v[18:19], v[0:1]
	v_mov_b64_e32 v[16:17], v[14:15]
	v_add_u32_e32 v123, 2, v122
	s_mov_b32 s47, 0
	v_mov_b32_e32 v120, 0
	v_mov_b32_e32 v128, 0xf149f2ca
	s_mov_b32 s34, 64
	s_mov_b64 s[30:31], 0
	v_mov_b64_e32 v[14:15], v[12:13]
	v_mov_b64_e32 v[12:13], v[10:11]
	v_mov_b64_e32 v[10:11], v[8:9]
	v_mov_b64_e32 v[8:9], v[6:7]
	v_mov_b64_e32 v[6:7], v[4:5]
	v_mov_b64_e32 v[4:5], v[2:3]
	v_mov_b64_e32 v[2:3], v[0:1]
	s_waitcnt lgkmcnt(0)
	s_barrier
	v_readlane_b32 s98, v255, 33
	s_nop 3
	s_cmp_eq_u32 s98, 0
	s_cbranch_scc1 .LBB0_546
	s_barrier
	s_branch .LBB0_546

; DI void fox_attn(const Params& P, int bh, int qb, unsigned char* smem, int tt) {
;     ...
;         {
;             const float sh = cq - m;
;             const f32x2v sh2 = {sh, sh};
;             f32x2v rs2 = {0.f, 0.f};
; #pragma unroll
;             for (int mt = 0; mt < 2; ++mt)
; #pragma unroll
;                 for (int p2 = 0; p2 < 8; ++p2) {
;                     const f32x2v sv = {sacc[mt][2 * p2], sacc[mt][2 * p2 + 1]};
;                     const f32x2v t = sv + sh2;
;                     f32x2v pp; pp.x = __builtin_amdgcn_exp2f(t.x); pp.y = __builtin_amdgcn_exp2f(t.y);
;                     sacc[mt][2 * p2] = pp.x; sacc[mt][2 * p2 + 1] = pp.y;
;                     rs2 = rs2 + pp;
;                 }
;             l += rs2.x + rs2.y;
;         }
;         {
;             u32x4 vw[2][2][2];
; #pragma unroll
;             for (int mt = 0; mt < 2; ++mt)
; #pragma unroll
;                 for (int s = 0; s < 2; ++s)
; #pragma unroll
;                     for (int dt = 0; dt < 2; ++dt) {
;                         const bf16_t* vp = VTs + (dt * 32 + r) * 72 + mt * 32 + 16 * s + 4 * h2;
;                         const u32x2 lo = *(const u32x2*)vp, hi = *(const u32x2*)(vp + 8);
;                         vw[mt][s][dt].x = lo.x; vw[mt][s][dt].y = lo.y; vw[mt][s][dt].z = hi.x; vw[mt][s][dt].w = hi.y;
;                     }
;             u32x4 pw[2][2];
; #pragma unroll
;             for (int mt = 0; mt < 2; ++mt)
; #pragma unroll
;                 for (int s = 0; s < 2; ++s) {
;                     pw[mt][s].x = pack2(sacc[mt][8 * s + 0], sacc[mt][8 * s + 1]); pw[mt][s].y = pack2(sacc[mt][8 * s + 2], sacc[mt][8 * s + 3]);
;                     pw[mt][s].z = pack2(sacc[mt][8 * s + 4], sacc[mt][8 * s + 5]); pw[mt][s].w = pack2(sacc[mt][8 * s + 6], sacc[mt][8 * s + 7]);
;                 }
;             __builtin_amdgcn_sched_barrier(0);
; #pragma unroll
;             for (int mt = 0; mt < 2; ++mt)
; #pragma unroll
;                 for (int s = 0; s < 2; ++s) {
;                     const bf16x8 pf = __builtin_bit_cast(bf16x8, pw[mt][s]);
;                     O[0] = MFMA32(__builtin_bit_cast(bf16x8, vw[mt][s][0]), pf, O[0]);
;                     O[1] = MFMA32(__builtin_bit_cast(bf16x8, vw[mt][s][1]), pf, O[1]);
;                 }
;         }
;         if (more) {
;             unsigned char* bufn = smem + ((kt + 1) & 1) * BUFB;
.LBB0_554:
	s_barrier
	v_sub_f32_e32 v132, v121, v128
	v_pk_add_f32 v[44:45], v[110:111], v[132:133] op_sel_hi:[1,0]
	v_lshlrev_b32_e32 v110, 1, v124
	v_add3_u32 v0, v0, v126, v110
	v_add_u32_e32 v129, 0x2000, v0
	v_add_u32_e32 v0, 0x3000, v0
	v_pk_add_f32 v[46:47], v[50:51], v[132:133] op_sel_hi:[1,0]
	v_pk_add_f32 v[48:49], v[114:115], v[132:133] op_sel_hi:[1,0]
	v_pk_add_f32 v[50:51], v[54:55], v[132:133] op_sel_hi:[1,0]
	v_pk_add_f32 v[54:55], v[112:113], v[132:133] op_sel_hi:[1,0]
	v_pk_add_f32 v[58:59], v[58:59], v[132:133] op_sel_hi:[1,0]
	v_pk_add_f32 v[64:65], v[116:117], v[132:133] op_sel_hi:[1,0]
	v_pk_add_f32 v[56:57], v[56:57], v[132:133] op_sel_hi:[1,0]
	v_pk_add_f32 v[62:63], v[62:63], v[132:133] op_sel_hi:[1,0]
	v_pk_add_f32 v[52:53], v[52:53], v[132:133] op_sel_hi:[1,0]
	v_pk_add_f32 v[60:61], v[60:61], v[132:133] op_sel_hi:[1,0]
	v_pk_add_f32 v[38:39], v[38:39], v[132:133] op_sel_hi:[1,0]
	v_pk_add_f32 v[42:43], v[42:43], v[132:133] op_sel_hi:[1,0]
	v_pk_add_f32 v[36:37], v[36:37], v[132:133] op_sel_hi:[1,0]
	v_pk_add_f32 v[40:41], v[40:41], v[132:133] op_sel_hi:[1,0]
	v_pk_add_f32 v[34:35], v[34:35], v[132:133] op_sel_hi:[1,0]
	ds_read2_b64 v[110:113], v129 offset0:128 offset1:130
	ds_read2_b64 v[114:117], v129 offset0:132 offset1:134
	ds_read2_b64 v[132:135], v0 offset0:192 offset1:194
	ds_read2_b64 v[136:139], v0 offset0:196 offset1:198
	ds_read2_b64 v[140:143], v129 offset0:136 offset1:138
	ds_read2_b64 v[144:147], v0 offset0:200 offset1:202
	ds_read2_b64 v[148:151], v129 offset0:140 offset1:142
	ds_read2_b64 v[152:155], v0 offset0:204 offset1:206
	v_exp_f32_e32 v44, v44
	v_exp_f32_e32 v45, v45
	v_exp_f32_e32 v46, v46
	v_exp_f32_e32 v47, v47
	v_exp_f32_e32 v48, v48
	v_exp_f32_e32 v49, v49
	v_exp_f32_e32 v50, v50
	v_exp_f32_e32 v51, v51
	v_exp_f32_e32 v54, v54
	v_exp_f32_e32 v55, v55
	v_exp_f32_e32 v58, v58
	v_exp_f32_e32 v59, v59
	v_exp_f32_e32 v64, v64
	v_exp_f32_e32 v65, v65
	v_exp_f32_e32 v56, v56
	v_exp_f32_e32 v57, v57
	v_exp_f32_e32 v62, v62
	v_exp_f32_e32 v63, v63
	v_exp_f32_e32 v52, v52
	v_exp_f32_e32 v53, v53
	v_exp_f32_e32 v60, v60
	v_exp_f32_e32 v61, v61
	v_exp_f32_e32 v38, v38
	v_exp_f32_e32 v39, v39
	v_exp_f32_e32 v42, v42
	v_exp_f32_e32 v43, v43
	v_exp_f32_e32 v36, v36
	v_exp_f32_e32 v37, v37
	v_exp_f32_e32 v40, v40
	v_exp_f32_e32 v41, v41
	v_exp_f32_e32 v34, v34
	v_exp_f32_e32 v35, v35
	v_cvt_pk_bf16_f32 v156, v44, v45
	v_cvt_pk_bf16_f32 v157, v46, v47
	v_cvt_pk_bf16_f32 v158, v48, v49
	v_cvt_pk_bf16_f32 v159, v50, v51
	v_cvt_pk_bf16_f32 v160, v54, v55
	v_cvt_pk_bf16_f32 v161, v58, v59
	v_cvt_pk_bf16_f32 v162, v64, v65
	v_cvt_pk_bf16_f32 v163, v56, v57
	v_cvt_pk_bf16_f32 v170, v62, v63
	v_cvt_pk_bf16_f32 v171, v52, v53
	v_cvt_pk_bf16_f32 v172, v60, v61
	v_cvt_pk_bf16_f32 v173, v38, v39
	v_cvt_pk_bf16_f32 v174, v42, v43
	v_cvt_pk_bf16_f32 v175, v36, v37
	v_cvt_pk_bf16_f32 v176, v40, v41
	v_cvt_pk_bf16_f32 v177, v34, v35
	s_waitcnt lgkmcnt(7)
	v_mfma_f32_32x32x16_bf16 v[18:33], v[110:113], v[156:159], v[18:33]
	s_waitcnt lgkmcnt(5)
	v_mfma_f32_32x32x16_bf16 v[2:17], v[132:135], v[156:159], v[2:17]
	v_mfma_f32_32x32x16_bf16 v[18:33], v[114:117], v[160:163], v[18:33]
	s_waitcnt lgkmcnt(4)
	v_mfma_f32_32x32x16_bf16 v[2:17], v[136:139], v[160:163], v[2:17]
	s_waitcnt lgkmcnt(3)
	v_mfma_f32_32x32x16_bf16 v[18:33], v[140:143], v[170:173], v[18:33]
	s_waitcnt lgkmcnt(2)
	v_mfma_f32_32x32x16_bf16 v[2:17], v[144:147], v[170:173], v[2:17]
	s_waitcnt lgkmcnt(1)
	v_mfma_f32_32x32x16_bf16 v[18:33], v[148:151], v[174:177], v[18:33]
	s_waitcnt lgkmcnt(0)
	v_mfma_f32_32x32x16_bf16 v[2:17], v[152:155], v[174:177], v[2:17]
	s_and_saveexec_b64 s[36:37], s[2:3]
	s_cbranch_execz .LBB0_545
	s_bitcmp1_b32 s47, 0
	s_cselect_b32 s2, 0x4900, 0
	v_add_u32_e32 v0, s2, v131
	v_add3_u32 v110, v0, v119, v104
	s_waitcnt vmcnt(3)
	ds_write_b128 v110, v[82:85]
	s_waitcnt vmcnt(2)
	ds_write_b128 v110, v[86:89] offset:4608
	s_waitcnt vmcnt(1)
	ds_write_b128 v110, v[90:93] offset:9216
	s_waitcnt vmcnt(0)
	ds_write_b128 v110, v[94:97] offset:13824
	s_and_b64 exec, exec, s[0:1]
	s_cbranch_execz .LBB0_545
	v_mul_f32_e32 v118, 0x3fb8aa3b, v118
	v_lshl_add_u32 v0, v130, 2, v0
	ds_write_b32 v0, v118 offset:18432
	s_branch .LBB0_545
.LBB0_557:
	s_or_b64 exec, exec, s[30:31]
	s_cmp_lg_u32 s98, 0
	s_cbranch_scc1 .Lfox_stag_done
	s_barrier
; DI unsigned pack2(float lo, float hi) { f32x2_t v = {lo, hi}; bf16x2_t b = __builtin_convertvector(v, bf16x2_t); return __builtin_bit_cast(unsigned, b); }
; DI float shx(float v, int mask, int lane) { return __int_as_float(__builtin_amdgcn_ds_bpermute((lane ^ mask) << 2, __float_as_int(v))); }
; DI void fox_attn(const Params& P, int bh, int qb, unsigned char* smem, int tt) {
;     ...
;     l += shx(l, 32, lane);
;     const float inv = 1.f / l;
;     float ss = 0.f;
; #pragma unroll
;     for (int e = 0; e < 16; ++e) { O[0][e] *= inv; O[1][e] *= inv; ss += O[0][e] * O[0][e] + O[1][e] * O[1][e]; }
;     ss += shx(ss, 32, lane);
;     const float sc = rsqrtf(ss * (1.f / 64.f) + 1e-6f);
;     bf16_t* op = (bf16_t*)(P.ws + OFF_MIX) + ((size_t)b * TSEQ + q) * 1024 + 512 + hh * 64;
;     const float* fg = P.in[10];
;     f32x4 ggv[2][4];
; #pragma unroll
;     for (int dt = 0; dt < 2; ++dt)
; #pragma unroll
;         for (int g = 0; g < 4; ++g) ggv[dt][g] = *(const f32x4*)(fg + dt * 32 + 8 * g + 4 * h2);
; #pragma unroll
;     for (int dt = 0; dt < 2; ++dt)
; #pragma unroll
;         for (int g = 0; g < 4; ++g) {
;             const int d0 = dt * 32 + 8 * g + 4 * h2;
;             const f32x4 gg = ggv[dt][g];
;             u32x2 o;
;             o.x = pack2(O[dt][4 * g + 0] * sc * gg[0], O[dt][4 * g + 1] * sc * gg[1]); o.y = pack2(O[dt][4 * g + 2] * sc * gg[2], O[dt][4 * g + 3] * sc * gg[3]);
;             *(u32x2*)(op + d0) = o;
;         }
.Lfox_stag_done:
	ds_bpermute_b32 v0, v99, v120
	v_lshlrev_b32_e32 v54, 2, v105
	global_load_dwordx4 v[34:37], v54, s[48:49]
	s_waitcnt lgkmcnt(0)
	v_add_f32_e32 v0, v120, v0
	v_div_scale_f32 v38, s[0:1], v0, v0, 1.0
	v_rcp_f32_e32 v39, v38
	v_div_scale_f32 v40, vcc, 1.0, v0, 1.0
	s_mov_b32 s0, 0x800000
	v_fma_f32 v41, -v38, v39, 1.0
	v_fmac_f32_e32 v39, v41, v39
	v_mul_f32_e32 v41, v40, v39
	v_fma_f32 v42, -v38, v41, v40
	v_fmac_f32_e32 v41, v42, v39
	v_fma_f32 v38, -v38, v41, v40
	v_div_fmas_f32 v38, v38, v39, v41
	v_div_fixup_f32 v0, v38, v0, 1.0
	v_pk_mul_f32 v[60:61], v[12:13], v[0:1] op_sel_hi:[1,0]
	v_pk_mul_f32 v[58:59], v[28:29], v[0:1] op_sel_hi:[1,0]
	v_pk_mul_f32 v[12:13], v[60:61], v[60:61]
	v_pk_mul_f32 v[66:67], v[14:15], v[0:1] op_sel_hi:[1,0]
	v_pk_fma_f32 v[62:63], v[58:59], v[58:59], v[12:13]
	v_pk_mul_f32 v[64:65], v[30:31], v[0:1] op_sel_hi:[1,0]
	v_pk_mul_f32 v[12:13], v[66:67], v[66:67]
	v_pk_mul_f32 v[16:17], v[16:17], v[0:1] op_sel_hi:[1,0]
	global_load_dwordx4 v[38:41], v54, s[48:49] offset:32
	v_pk_fma_f32 v[68:69], v[64:65], v[64:65], v[12:13]
	v_pk_mul_f32 v[32:33], v[32:33], v[0:1] op_sel_hi:[1,0]
	v_pk_mul_f32 v[12:13], v[16:17], v[16:17]
	v_pk_mul_f32 v[2:3], v[2:3], v[0:1] op_sel_hi:[1,0]
	v_pk_fma_f32 v[70:71], v[32:33], v[32:33], v[12:13]
	global_load_dwordx4 v[12:15], v54, s[48:49] offset:64
	global_load_dwordx4 v[28:31], v54, s[48:49] offset:96
	global_load_dwordx4 v[42:45], v54, s[48:49] offset:128
	global_load_dwordx4 v[46:49], v54, s[48:49] offset:160
	global_load_dwordx4 v[50:53], v54, s[48:49] offset:192
	s_nop 0
	global_load_dwordx4 v[54:57], v54, s[48:49] offset:224
	v_pk_mul_f32 v[18:19], v[18:19], v[0:1] op_sel_hi:[1,0]
	v_pk_mul_f32 v[4:5], v[4:5], v[0:1] op_sel_hi:[1,0]
	v_pk_mul_f32 v[74:75], v[2:3], v[2:3]
	v_pk_mul_f32 v[20:21], v[20:21], v[0:1] op_sel_hi:[1,0]
	v_pk_mul_f32 v[72:73], v[4:5], v[4:5]
	v_pk_fma_f32 v[74:75], v[18:19], v[18:19], v[74:75]
	v_pk_mul_f32 v[24:25], v[24:25], v[0:1] op_sel_hi:[1,0]
	v_pk_mul_f32 v[22:23], v[22:23], v[0:1] op_sel_hi:[1,0]
	v_pk_mul_f32 v[26:27], v[26:27], v[0:1] op_sel_hi:[1,0]
	v_pk_fma_f32 v[72:73], v[20:21], v[20:21], v[72:73]
	v_pk_mul_f32 v[8:9], v[8:9], v[0:1] op_sel_hi:[1,0]
	v_pk_mul_f32 v[6:7], v[6:7], v[0:1] op_sel_hi:[1,0]
	v_pk_mul_f32 v[10:11], v[10:11], v[0:1] op_sel_hi:[1,0]
	v_add_f32_e32 v0, v74, v75
	v_pk_mul_f32 v[78:79], v[6:7], v[6:7]
	v_add_f32_e32 v0, v72, v0
	v_pk_fma_f32 v[78:79], v[22:23], v[22:23], v[78:79]
	v_add_f32_e32 v0, v73, v0
	v_pk_mul_f32 v[76:77], v[8:9], v[8:9]
	v_add_f32_e32 v0, v78, v0
	v_pk_fma_f32 v[76:77], v[24:25], v[24:25], v[76:77]
	v_add_f32_e32 v0, v79, v0
	v_pk_mul_f32 v[80:81], v[10:11], v[10:11]
	v_add_f32_e32 v0, v76, v0
	v_pk_fma_f32 v[80:81], v[26:27], v[26:27], v[80:81]
	v_add_f32_e32 v0, v77, v0
	v_add_f32_e32 v0, v80, v0
	v_add_f32_e32 v0, v81, v0
	v_add_f32_e32 v0, v62, v0
	v_add_f32_e32 v0, v63, v0
	v_add_f32_e32 v0, v68, v0
	v_add_f32_e32 v0, v69, v0
	v_add_f32_e32 v0, v70, v0
	v_add_f32_e32 v0, v71, v0
	ds_bpermute_b32 v68, v99, v0
	v_lshl_add_u64 v[62:63], v[100:101], 1, s[80:81]
	v_mov_b32_e32 v99, v1
	v_lshl_add_u64 v[62:63], v[62:63], 0, v[98:99]
	s_waitcnt lgkmcnt(0)
	v_add_f32_e32 v0, v0, v68
	v_fmamk_f32 v0, v0, 0x3c800000, v166
	v_mul_f32_e32 v68, 0x4b800000, v0
	v_cmp_gt_f32_e32 vcc, s0, v0
	s_mov_b64 s[0:1], 0xd800400
	s_nop 0
	v_cndmask_b32_e32 v0, v0, v68, vcc
	v_rsq_f32_e32 v70, v0
	v_lshlrev_b32_e32 v0, 1, v105
	v_lshl_add_u64 v[62:63], v[62:63], 0, v[0:1]
	v_lshl_add_u64 v[68:69], v[62:63], 0, s[0:1]
	v_mul_f32_e32 v0, 0x45800000, v70
	v_cndmask_b32_e32 v0, v70, v0, vcc
	v_pk_mul_f32 v[18:19], v[18:19], v[0:1] op_sel_hi:[1,0]
	v_pk_mul_f32 v[20:21], v[20:21], v[0:1] op_sel_hi:[1,0]
	s_waitcnt vmcnt(7)
	v_pk_mul_f32 v[18:19], v[34:35], v[18:19]
	v_pk_mul_f32 v[20:21], v[36:37], v[20:21]
	s_mov_b32 s0, 0xd800000
	v_cvt_pk_bf16_f32 v18, v18, v19
	v_cvt_pk_bf16_f32 v19, v20, v21
	v_add_co_u32_e32 v20, vcc, s0, v62
	v_pk_mul_f32 v[2:3], v[2:3], v[0:1] op_sel_hi:[1,0]
	v_pk_mul_f32 v[4:5], v[4:5], v[0:1] op_sel_hi:[1,0]
	v_addc_co_u32_e32 v21, vcc, 0, v63, vcc
	global_store_dwordx2 v[20:21], v[18:19], off offset:1024
	v_pk_mul_f32 v[18:19], v[22:23], v[0:1] op_sel_hi:[1,0]
	v_pk_mul_f32 v[20:21], v[24:25], v[0:1] op_sel_hi:[1,0]
	s_waitcnt vmcnt(7)
	v_pk_mul_f32 v[18:19], v[38:39], v[18:19]
	v_pk_mul_f32 v[20:21], v[40:41], v[20:21]
	v_cvt_pk_bf16_f32 v18, v18, v19
	s_waitcnt vmcnt(4)
	v_pk_mul_f32 v[2:3], v[42:43], v[2:3]
	v_pk_mul_f32 v[4:5], v[44:45], v[4:5]
	v_cvt_pk_bf16_f32 v2, v2, v3
	v_cvt_pk_bf16_f32 v3, v4, v5
	global_store_dwordx2 v[68:69], v[2:3], off offset:64
	v_pk_mul_f32 v[2:3], v[6:7], v[0:1] op_sel_hi:[1,0]
	v_pk_mul_f32 v[4:5], v[8:9], v[0:1] op_sel_hi:[1,0]
	v_cvt_pk_bf16_f32 v19, v20, v21
	s_waitcnt vmcnt(4)
	v_pk_mul_f32 v[2:3], v[46:47], v[2:3]
	v_pk_mul_f32 v[4:5], v[48:49], v[4:5]
	global_store_dwordx2 v[68:69], v[18:19], off offset:16
	v_pk_mul_f32 v[18:19], v[26:27], v[0:1] op_sel_hi:[1,0]
	v_cvt_pk_bf16_f32 v2, v2, v3
	v_cvt_pk_bf16_f32 v3, v4, v5
	v_pk_mul_f32 v[12:13], v[12:13], v[18:19]
	v_pk_mul_f32 v[18:19], v[58:59], v[0:1] op_sel_hi:[1,0]
	global_store_dwordx2 v[68:69], v[2:3], off offset:80
	v_pk_mul_f32 v[2:3], v[10:11], v[0:1] op_sel_hi:[1,0]
	v_pk_mul_f32 v[4:5], v[60:61], v[0:1] op_sel_hi:[1,0]
	v_pk_mul_f32 v[14:15], v[14:15], v[18:19]
	s_waitcnt vmcnt(5)
	v_pk_mul_f32 v[2:3], v[50:51], v[2:3]
	v_pk_mul_f32 v[4:5], v[52:53], v[4:5]
	v_cvt_pk_bf16_f32 v12, v12, v13
	v_cvt_pk_bf16_f32 v13, v14, v15
	v_cvt_pk_bf16_f32 v2, v2, v3
	v_cvt_pk_bf16_f32 v3, v4, v5
	global_store_dwordx2 v[68:69], v[12:13], off offset:32
	v_pk_mul_f32 v[12:13], v[64:65], v[0:1] op_sel_hi:[1,0]
	v_pk_mul_f32 v[14:15], v[32:33], v[0:1] op_sel_hi:[1,0]
	global_store_dwordx2 v[68:69], v[2:3], off offset:96
	v_pk_mul_f32 v[2:3], v[66:67], v[0:1] op_sel_hi:[1,0]
	v_pk_mul_f32 v[4:5], v[16:17], v[0:1] op_sel_hi:[1,0]
	v_pk_mul_f32 v[12:13], v[28:29], v[12:13]
	v_pk_mul_f32 v[14:15], v[30:31], v[14:15]
	s_waitcnt vmcnt(6)
	v_pk_mul_f32 v[2:3], v[54:55], v[2:3]
	v_pk_mul_f32 v[4:5], v[56:57], v[4:5]
	v_cvt_pk_bf16_f32 v12, v12, v13
	v_cvt_pk_bf16_f32 v13, v14, v15
	v_cvt_pk_bf16_f32 v2, v2, v3
	v_cvt_pk_bf16_f32 v3, v4, v5
	global_store_dwordx2 v[68:69], v[12:13], off offset:48
	global_store_dwordx2 v[68:69], v[2:3], off offset:112

; __global__ void __launch_bounds__(512, 2) fwd_mega(Params P) {
	.amdhsa_kernel _Z8fwd_mega6Params
		.amdhsa_group_segment_fixed_size 0
		.amdhsa_private_segment_fixed_size 0
		.amdhsa_kernarg_size 440
		.amdhsa_user_sgpr_count 2
		.amdhsa_user_sgpr_dispatch_ptr 0
		.amdhsa_user_sgpr_queue_ptr 0
		.amdhsa_user_sgpr_kernarg_segment_ptr 1
		.amdhsa_user_sgpr_dispatch_id 0
		.amdhsa_user_sgpr_kernarg_preload_length 0
		.amdhsa_user_sgpr_kernarg_preload_offset 0
		.amdhsa_user_sgpr_private_segment_size 0
		.amdhsa_uses_dynamic_stack 0
		.amdhsa_enable_private_segment 0
		.amdhsa_system_sgpr_workgroup_id_x 1
		.amdhsa_system_sgpr_workgroup_id_y 0
		.amdhsa_system_sgpr_workgroup_id_z 0
		.amdhsa_system_sgpr_workgroup_info 0
		.amdhsa_system_vgpr_workitem_id 2
		.amdhsa_next_free_vgpr 256
		.amdhsa_next_free_sgpr 100
		.amdhsa_accum_offset 256
		.amdhsa_reserve_vcc 1
		.amdhsa_float_round_mode_32 0
		.amdhsa_float_round_mode_16_64 0
		.amdhsa_float_denorm_mode_32 3
		.amdhsa_float_denorm_mode_16_64 3
		.amdhsa_dx10_clamp 1
		.amdhsa_ieee_mode 1
		.amdhsa_fp16_overflow 0
		.amdhsa_tg_split 0
		.amdhsa_exception_fp_ieee_invalid_op 0
		.amdhsa_exception_fp_denorm_src 0
		.amdhsa_exception_fp_ieee_div_zero 0
		.amdhsa_exception_fp_ieee_overflow 0
		.amdhsa_exception_fp_ieee_underflow 0
		.amdhsa_exception_fp_ieee_inexact 0
		.amdhsa_exception_int_div_zero 0
	.end_amdhsa_kernel

; __global__ void __launch_bounds__(512, 2) fwd_mega(Params P) {
amdhsa.kernels:
  - .agpr_count:     0
    .args:
      - .offset:         0
        .size:           184
        .value_kind:     by_value
      - .offset:         184
        .size:           4
        .value_kind:     hidden_block_count_x
      - .offset:         188
        .size:           4
        .value_kind:     hidden_block_count_y
      - .offset:         192
        .size:           4
        .value_kind:     hidden_block_count_z
      - .offset:         196
        .size:           2
        .value_kind:     hidden_group_size_x
      - .offset:         198
        .size:           2
        .value_kind:     hidden_group_size_y
      - .offset:         200
        .size:           2
        .value_kind:     hidden_group_size_z
      - .offset:         202
        .size:           2
        .value_kind:     hidden_remainder_x
      - .offset:         204
        .size:           2
        .value_kind:     hidden_remainder_y
      - .offset:         206
        .size:           2
        .value_kind:     hidden_remainder_z
      - .offset:         224
        .size:           8
        .value_kind:     hidden_global_offset_x
      - .offset:         232
        .size:           8
        .value_kind:     hidden_global_offset_y
      - .offset:         240
        .size:           8
        .value_kind:     hidden_global_offset_z
      - .offset:         248
        .size:           2
        .value_kind:     hidden_grid_dims
      - .offset:         272
        .size:           8
        .value_kind:     hidden_multigrid_sync_arg
      - .offset:         304
        .size:           4
        .value_kind:     hidden_dynamic_lds_size
    .group_segment_fixed_size: 0
    .kernarg_segment_align: 8
    .kernarg_segment_size: 440
    .language:       OpenCL C
    .language_version:
      - 2
      - 0
    .max_flat_workgroup_size: 512
    .name:           _Z8fwd_mega6Params
    .private_segment_fixed_size: 0
    .sgpr_count:     106
    .sgpr_spill_count: 50
    .symbol:         _Z8fwd_mega6Params.kd
    .uniform_work_group_size: 1
    .uses_dynamic_stack: false
    .vgpr_count:     256
    .vgpr_spill_count: 0
    .wavefront_size: 64
